# attention softmax body hand-rewritten: in-place sub/exp, packed-add sum tree, 16 cvt_pk with no pk_mov shuffles, V fragment reads issued before the max tree into the free K-ring registers
# speedup vs baseline: 1.0056x; 1.0026x over previous
; __device__ __forceinline__ void attn_unit(const Params& p, int b, int h, int qb, unsigned char* lds) {
;     ...
;             float mx = fmaxf(s0[0], s1[0]);
; #pragma unroll
;             for (int r = 1; r < 16; ++r) mx = fmaxf(mx, fmaxf(s0[r], s1[r]));
;             mx = fmaxf(mx, __shfl_xor(mx, 32));
;             if (__any(mx > m_run + 8.f)) {
;                 const float m_new = fmaxf(m_run, mx), alpha = __builtin_amdgcn_exp2f(m_run - m_new); m_run = m_new;
;                 l_run *= alpha;
; #pragma unroll
;                 for (int d = 0; d < 4; ++d)
; #pragma unroll
;                     for (int r = 0; r < 16; ++r) o[d][r] *= alpha;
;             }
;     ...
;             bf16x8 va[4];
; #pragma unroll
;             for (int i = 0; i < 4; ++i) va[i] = *(const bf16x8*)(Vb + (i >> 2) * 32 * AV_STRIDE + (i & 3) * 32);
.LBB0_502:
	s_mul_i32 s36, s35, 0x4800
	v_add_u32_e32 v246, s36, v220
	ds_read_b128 v[230:233], v246 offset:51200
	ds_read_b128 v[234:237], v246 offset:51232
	ds_read_b128 v[238:241], v246 offset:51264
	ds_read_b128 v[242:245], v246 offset:51296
	s_nop 2
	v_max3_f32 v225, v66, v67, v68
	v_max3_f32 v226, v69, v70, v71
	v_max3_f32 v227, v72, v73, v74
	v_max3_f32 v228, v75, v76, v77
	v_max3_f32 v225, v225, v78, v79
	v_max3_f32 v226, v226, v80, v81
	v_max3_f32 v227, v227, v82, v83
	v_max3_f32 v228, v228, v84, v85
	v_max3_f32 v225, v225, v86, v87
	v_max3_f32 v226, v226, v88, v89
	v_max3_f32 v227, v227, v90, v91
	v_max3_f32 v228, v228, v92, v93
	v_max3_f32 v225, v225, v94, v95
	v_max3_f32 v226, v226, v96, v97
	v_max3_f32 v225, v225, v226, v227
	v_max_f32_e32 v225, v225, v228
	v_mov_b32_e32 v226, v225
	s_nop 1
	v_permlane32_swap_b32_e32 v225, v226
	v_max_f32_e32 v225, v225, v226
	v_add_f32_e32 v226, 0x41000000, v191
	v_cmp_gt_f32_e32 vcc, v225, v226
	s_cbranch_vccz .LBB0_504
	v_max_f32_e32 v225, v225, v225
	v_max_f32_e32 v226, v191, v191
	v_max_f32_e32 v225, v226, v225
	v_sub_f32_e32 v191, v191, v225
	v_exp_f32_e32 v226, v191
	v_mov_b32_e32 v191, v225
	v_pk_mul_f32 v[64:65], v[64:65], v[226:227] op_sel_hi:[1,0]
	v_pk_mul_f32 v[62:63], v[62:63], v[226:227] op_sel_hi:[1,0]
	v_pk_mul_f32 v[60:61], v[60:61], v[226:227] op_sel_hi:[1,0]
	v_pk_mul_f32 v[58:59], v[58:59], v[226:227] op_sel_hi:[1,0]
	v_pk_mul_f32 v[56:57], v[56:57], v[226:227] op_sel_hi:[1,0]
	v_pk_mul_f32 v[54:55], v[54:55], v[226:227] op_sel_hi:[1,0]
	v_pk_mul_f32 v[52:53], v[52:53], v[226:227] op_sel_hi:[1,0]
	v_pk_mul_f32 v[50:51], v[50:51], v[226:227] op_sel_hi:[1,0]
	v_pk_mul_f32 v[48:49], v[48:49], v[226:227] op_sel_hi:[1,0]
	v_pk_mul_f32 v[46:47], v[46:47], v[226:227] op_sel_hi:[1,0]
	v_pk_mul_f32 v[44:45], v[44:45], v[226:227] op_sel_hi:[1,0]
	v_pk_mul_f32 v[42:43], v[42:43], v[226:227] op_sel_hi:[1,0]
	v_pk_mul_f32 v[40:41], v[40:41], v[226:227] op_sel_hi:[1,0]
	v_pk_mul_f32 v[38:39], v[38:39], v[226:227] op_sel_hi:[1,0]
	v_pk_mul_f32 v[36:37], v[36:37], v[226:227] op_sel_hi:[1,0]
	v_pk_mul_f32 v[34:35], v[34:35], v[226:227] op_sel_hi:[1,0]
	v_pk_mul_f32 v[32:33], v[32:33], v[226:227] op_sel_hi:[1,0]
	v_pk_mul_f32 v[30:31], v[30:31], v[226:227] op_sel_hi:[1,0]
	v_pk_mul_f32 v[28:29], v[28:29], v[226:227] op_sel_hi:[1,0]
	v_pk_mul_f32 v[26:27], v[26:27], v[226:227] op_sel_hi:[1,0]
	v_pk_mul_f32 v[24:25], v[24:25], v[226:227] op_sel_hi:[1,0]
	v_pk_mul_f32 v[22:23], v[22:23], v[226:227] op_sel_hi:[1,0]
	v_pk_mul_f32 v[20:21], v[20:21], v[226:227] op_sel_hi:[1,0]
	v_pk_mul_f32 v[18:19], v[18:19], v[226:227] op_sel_hi:[1,0]
	v_pk_mul_f32 v[16:17], v[16:17], v[226:227] op_sel_hi:[1,0]
	v_pk_mul_f32 v[14:15], v[14:15], v[226:227] op_sel_hi:[1,0]
	v_pk_mul_f32 v[12:13], v[12:13], v[226:227] op_sel_hi:[1,0]
	v_pk_mul_f32 v[10:11], v[10:11], v[226:227] op_sel_hi:[1,0]
	v_pk_mul_f32 v[8:9], v[8:9], v[226:227] op_sel_hi:[1,0]
	v_pk_mul_f32 v[6:7], v[6:7], v[226:227] op_sel_hi:[1,0]
	v_pk_mul_f32 v[4:5], v[4:5], v[226:227] op_sel_hi:[1,0]
	v_pk_mul_f32 v[2:3], v[2:3], v[226:227] op_sel_hi:[1,0]
	v_mul_f32_e32 v189, v189, v226
; __device__ __forceinline__ unsigned pk2(float lo, float hi) { return pg8::cvt_pk_bf16(lo, hi); }
; __device__ __forceinline__ void attn_unit(const Params& p, int b, int h, int qb, unsigned char* lds) {
;     ...
;             float sum = 0.f;
; #pragma unroll
;             for (int r = 0; r < 16; ++r) { s0[r] = __builtin_amdgcn_exp2f(s0[r] - m_run); s1[r] = __builtin_amdgcn_exp2f(s1[r] - m_run); sum += s0[r] + s1[r]; }
;             l_run += sum;
;             bf16x8 pb[2][2];
; #pragma unroll
;             for (int ks = 0; ks < 2; ++ks) {
;                 u32x4 w0, w1;
;                 w0.x = pk2(s0[8 * ks + 0], s0[8 * ks + 1]); w0.y = pk2(s0[8 * ks + 2], s0[8 * ks + 3]); w0.z = pk2(s0[8 * ks + 4], s0[8 * ks + 5]); w0.w = pk2(s0[8 * ks + 6], s0[8 * ks + 7]);
;                 w1.x = pk2(s1[8 * ks + 0], s1[8 * ks + 1]); w1.y = pk2(s1[8 * ks + 2], s1[8 * ks + 3]); w1.z = pk2(s1[8 * ks + 4], s1[8 * ks + 5]); w1.w = pk2(s1[8 * ks + 6], s1[8 * ks + 7]);
;                 pb[0][ks] = __builtin_bit_cast(bf16x8, w0); pb[1][ks] = __builtin_bit_cast(bf16x8, w1);
;             }
;             bf16x8 va[4];
; #pragma unroll
;             for (int i = 0; i < 4; ++i) va[i] = *(const bf16x8*)(Vb + (i >> 2) * 32 * AV_STRIDE + (i & 3) * 32);
;             __builtin_amdgcn_s_setprio(1);
; #pragma unroll
;             for (int i = 0; i < 16; ++i) {
;                 o[i >> 2] = __builtin_amdgcn_mfma_f32_32x32x16_bf16(va[i & 3], pb[(i >> 1) & 1][i & 1], o[i >> 2], 0, 0, 0);
;                 if (i + 4 < 16) va[i & 3] = *(const bf16x8*)(Vb + ((i + 4) >> 2) * 32 * AV_STRIDE + ((i + 4) & 3) * 32);
;                 __builtin_amdgcn_sched_barrier(0);
;             }
;             __builtin_amdgcn_s_setprio(0);
.LBB0_504:
	v_sub_f32_e32 v66, v66, v191
	v_sub_f32_e32 v67, v67, v191
	v_sub_f32_e32 v68, v68, v191
	v_sub_f32_e32 v69, v69, v191
	v_exp_f32_e32 v66, v66
	v_exp_f32_e32 v67, v67
	v_exp_f32_e32 v68, v68
	v_exp_f32_e32 v69, v69
	v_sub_f32_e32 v70, v70, v191
	v_sub_f32_e32 v71, v71, v191
	v_sub_f32_e32 v72, v72, v191
	v_sub_f32_e32 v73, v73, v191
	v_exp_f32_e32 v70, v70
	v_exp_f32_e32 v71, v71
	v_exp_f32_e32 v72, v72
	v_exp_f32_e32 v73, v73
	v_sub_f32_e32 v74, v74, v191
	v_sub_f32_e32 v75, v75, v191
	v_sub_f32_e32 v76, v76, v191
	v_sub_f32_e32 v77, v77, v191
	v_exp_f32_e32 v74, v74
	v_exp_f32_e32 v75, v75
	v_exp_f32_e32 v76, v76
	v_exp_f32_e32 v77, v77
	v_sub_f32_e32 v78, v78, v191
	v_sub_f32_e32 v79, v79, v191
	v_sub_f32_e32 v80, v80, v191
	v_sub_f32_e32 v81, v81, v191
	v_exp_f32_e32 v78, v78
	v_exp_f32_e32 v79, v79
	v_exp_f32_e32 v80, v80
	v_exp_f32_e32 v81, v81
	v_sub_f32_e32 v82, v82, v191
	v_sub_f32_e32 v83, v83, v191
	v_sub_f32_e32 v84, v84, v191
	v_sub_f32_e32 v85, v85, v191
	v_exp_f32_e32 v82, v82
	v_exp_f32_e32 v83, v83
	v_exp_f32_e32 v84, v84
	v_exp_f32_e32 v85, v85
	v_sub_f32_e32 v86, v86, v191
	v_sub_f32_e32 v87, v87, v191
	v_sub_f32_e32 v88, v88, v191
	v_sub_f32_e32 v89, v89, v191
	v_exp_f32_e32 v86, v86
	v_exp_f32_e32 v87, v87
	v_exp_f32_e32 v88, v88
	v_exp_f32_e32 v89, v89
	v_sub_f32_e32 v90, v90, v191
	v_sub_f32_e32 v91, v91, v191
	v_sub_f32_e32 v92, v92, v191
	v_sub_f32_e32 v93, v93, v191
	v_exp_f32_e32 v90, v90
	v_exp_f32_e32 v91, v91
	v_exp_f32_e32 v92, v92
	v_exp_f32_e32 v93, v93
	v_sub_f32_e32 v94, v94, v191
	v_sub_f32_e32 v95, v95, v191
	v_sub_f32_e32 v96, v96, v191
	v_sub_f32_e32 v97, v97, v191
	v_exp_f32_e32 v94, v94
	v_exp_f32_e32 v95, v95
	v_exp_f32_e32 v96, v96
	v_exp_f32_e32 v97, v97
	v_pk_add_f32 v[226:227], v[66:67], v[68:69]
	v_pk_add_f32 v[228:229], v[70:71], v[72:73]
	v_pk_add_f32 v[248:249], v[74:75], v[76:77]
	v_pk_add_f32 v[250:251], v[78:79], v[80:81]
	v_pk_add_f32 v[226:227], v[226:227], v[82:83]
	v_pk_add_f32 v[228:229], v[228:229], v[84:85]
	v_pk_add_f32 v[248:249], v[248:249], v[86:87]
	v_pk_add_f32 v[250:251], v[250:251], v[88:89]
	v_pk_add_f32 v[226:227], v[226:227], v[90:91]
	v_pk_add_f32 v[228:229], v[228:229], v[92:93]
	v_pk_add_f32 v[248:249], v[248:249], v[94:95]
	v_pk_add_f32 v[250:251], v[250:251], v[96:97]
	v_cvt_pk_bf16_f32 v66, v66, v67
	v_cvt_pk_bf16_f32 v67, v68, v69
	v_pk_add_f32 v[226:227], v[226:227], v[228:229]
	v_cvt_pk_bf16_f32 v68, v70, v71
	v_pk_add_f32 v[248:249], v[248:249], v[250:251]
	v_cvt_pk_bf16_f32 v69, v72, v73
	v_cvt_pk_bf16_f32 v74, v74, v75
	v_pk_add_f32 v[226:227], v[226:227], v[248:249]
	v_cvt_pk_bf16_f32 v75, v76, v77
	v_cvt_pk_bf16_f32 v76, v78, v79
	v_cvt_pk_bf16_f32 v77, v80, v81
	v_cvt_pk_bf16_f32 v70, v82, v83
	v_cvt_pk_bf16_f32 v71, v84, v85
	v_add_f32_e32 v225, v226, v227
	v_cvt_pk_bf16_f32 v72, v86, v87
	v_cvt_pk_bf16_f32 v73, v88, v89
	v_cvt_pk_bf16_f32 v78, v90, v91
	v_cvt_pk_bf16_f32 v79, v92, v93
	v_cvt_pk_bf16_f32 v80, v94, v95
	v_cvt_pk_bf16_f32 v81, v96, v97
	s_waitcnt lgkmcnt(3)
	v_mfma_f32_32x32x16_bf16 v[50:65], v[230:233], v[66:69], v[50:65]
	ds_read_b128 v[226:229], v246 offset:55808
	s_waitcnt lgkmcnt(3)
	v_mfma_f32_32x32x16_bf16 v[50:65], v[234:237], v[74:77], v[50:65]
	ds_read_b128 v[230:233], v246 offset:55840
	s_waitcnt lgkmcnt(3)
	v_mfma_f32_32x32x16_bf16 v[50:65], v[238:241], v[70:73], v[50:65]
	ds_read_b128 v[234:237], v246 offset:55872
	s_waitcnt lgkmcnt(3)
	v_mfma_f32_32x32x16_bf16 v[50:65], v[242:245], v[78:81], v[50:65]
	ds_read_b128 v[238:241], v246 offset:55904
	s_waitcnt lgkmcnt(3)
	v_mfma_f32_32x32x16_bf16 v[34:49], v[226:229], v[66:69], v[34:49]
	ds_read_b128 v[242:245], v246 offset:60416
	s_waitcnt lgkmcnt(3)
	v_mfma_f32_32x32x16_bf16 v[34:49], v[230:233], v[74:77], v[34:49]
	ds_read_b128 v[226:229], v246 offset:60448
	s_waitcnt lgkmcnt(3)
	v_mfma_f32_32x32x16_bf16 v[34:49], v[234:237], v[70:73], v[34:49]
	ds_read_b128 v[230:233], v246 offset:60480
	s_waitcnt lgkmcnt(3)
	v_mfma_f32_32x32x16_bf16 v[34:49], v[238:241], v[78:81], v[34:49]
	ds_read_b128 v[234:237], v246 offset:60512
	s_waitcnt lgkmcnt(3)
	v_mfma_f32_32x32x16_bf16 v[18:33], v[242:245], v[66:69], v[18:33]
	ds_read_b128 v[238:241], v246 offset:65024
	s_waitcnt lgkmcnt(3)
	v_mfma_f32_32x32x16_bf16 v[18:33], v[226:229], v[74:77], v[18:33]
	ds_read_b128 v[242:245], v246 offset:65056
	s_waitcnt lgkmcnt(3)
	v_mfma_f32_32x32x16_bf16 v[18:33], v[230:233], v[70:73], v[18:33]
	ds_read_b128 v[226:229], v246 offset:65088
	s_waitcnt lgkmcnt(3)
	v_mfma_f32_32x32x16_bf16 v[18:33], v[234:237], v[78:81], v[18:33]
	ds_read_b128 v[230:233], v246 offset:65120
	s_waitcnt lgkmcnt(3)
	v_mfma_f32_32x32x16_bf16 v[2:17], v[238:241], v[66:69], v[2:17]
	s_waitcnt lgkmcnt(2)
	v_mfma_f32_32x32x16_bf16 v[2:17], v[242:245], v[74:77], v[2:17]
	s_waitcnt lgkmcnt(1)
	v_mfma_f32_32x32x16_bf16 v[2:17], v[226:229], v[70:73], v[2:17]
	s_waitcnt lgkmcnt(0)
	v_mfma_f32_32x32x16_bf16 v[2:17], v[230:233], v[78:81], v[2:17]
	v_add_f32_e32 v189, v189, v225
	s_andn2_b64 vcc, exec, s[22:23]
	s_cbranch_vccz .LBB0_496
	s_branch .LBB0_497
